# attention B loop: K reads hoisted, stray vmcnt wait removed; static s_setprio 1 for waves 4-7 during attention
# speedup vs baseline: 1.0050x; 1.0050x over previous
; #define GRID_BAR() do { XcdBarrier bb_ = xbar; bb_.bar = (unsigned*)lau((unsigned char*)bb_.bar); bb_.x = (unsigned)lauint((int)bb_.x); xcd_barrier(bb_); } while (0)
; __global__ void __launch_bounds__(NWAVES * 64, 2) mega_fwd(Args args) {
;     ...
;     for (int ph = 0; ph < 26; ++ph) {
;     ...
;         GRID_BAR();
;     }
.LBB0_201:
	s_or_b64 exec, exec, s[42:43]
	s_setprio 0
	s_add_i32 s16, s16, 1
	s_cmp_eq_u32 s16, 26
	s_waitcnt lgkmcnt(0)
	s_barrier
	s_cbranch_scc1 .LBB0_815

; __global__ void __launch_bounds__(NWAVES * 64, 2) mega_fwd(Args args) {
;     ...
;                 for (int rep = 0; rep < ATT_REP; ++rep) if (k == 7 && PH_ON(6)) { PTRS
;                     const int b = vcu >> 3, jj = vcu & 7; const size_t r0 = (size_t)b * SEQ;
; #pragma unroll 1
;                     for (int i = 0; i < 6; ++i) { const int e = (jj & 3) * 6 + i, h = (jj >> 2) * 3 + (e >> 3), qb = e & 7, kvh = jj >> 2;
;                         att::Desc d{YS + r0 * NYS + h * 64, NYS, YS + r0 * NYS + 384 + kvh * 64, NYS, nullptr, 0, YS + r0 * NYS + 512 + kvh * 64, NYS, AP + r0 * DM + h * 64, DM};
;                         att::unit<64, 0>(d, qb * 256, (att::ATT_LAS_T)lds, nullptr, 0.f); }
.LBB0_525:
	s_cmp_gt_i32 s17, 1
	s_mov_b64 s[4:5], -1
	s_cbranch_scc0 .LBB0_627
	s_cmp_gt_i32 s17, 6
	s_cbranch_scc0 .LBB0_624
	v_readfirstlane_b32 s3, v228
	s_lshr_b32 s3, s3, 8
	s_cmp_eq_u32 s3, 0
	s_cbranch_scc1 .Lprio_done
	s_setprio 1
.Lprio_done:
	v_mov_b32_e32 v0, v228
	s_load_dwordx2 s[18:19], s[0:1], 0xd0
	s_waitcnt lgkmcnt(0)
	s_load_dwordx2 s[4:5], s[0:1], 0xc8
	s_waitcnt lgkmcnt(0)
	v_readlane_b32 s3, v254, 56
	s_add_u32 s3, s18, s3
	v_readlane_b32 s4, v254, 60
	s_addc_u32 s4, s19, s4
	s_add_u32 s22, s3, 0xf000000
	s_addc_u32 s23, s4, 0
	v_readlane_b32 s3, v255, 5
	s_add_u32 s24, s22, s3
	s_addc_u32 s25, s23, 0
	v_readlane_b32 s4, v254, 24
	v_readlane_b32 s5, v254, 25
	s_add_u32 s3, s18, s4
	s_addc_u32 s4, s19, s5
	s_add_u32 s52, s3, 0x7000000
	s_addc_u32 s53, s4, 0
	v_readlane_b32 s3, v254, 57
	s_add_u32 s26, s18, s3
	v_readlane_b32 s3, v254, 58
	s_addc_u32 s27, s19, s3
	v_readlane_b32 s3, v254, 59
	s_add_u32 s3, s18, s3
	v_readlane_b32 s4, v254, 61
	s_addc_u32 s10, s19, s4
	s_mov_b32 s11, 0
	s_branch .LBB0_529

; #define ATT_LAS __attribute__((address_space(3)))
; template <int DQK, int MODE> __device__ __forceinline__ void unit(const Desc& d, int q0, ATT_LAS char* shm, const float* biasg, float sinkl2) {
;     ...
;             { const ATT_LAS char* kb = shm + LDS_K + buf * KSLOT + hi * 1024 + r32 * 16;
; #pragma unroll
;               for (int d0 = 0; d0 < ND0; ++d0) {
;                   const bf16x8 b0 = *(const ATT_LAS bf16x8*)(kb + d0 * 2048);
;                   const bf16x8 b1 = *(const ATT_LAS bf16x8*)(kb + d0 * 2048 + 512);
;                   if (d0 == 0) { p0 = __builtin_amdgcn_mfma_f32_32x32x16_bf16(b0, qr[0], negm, 0, 0, 0); p1 = __builtin_amdgcn_mfma_f32_32x32x16_bf16(b1, qr[0], negm, 0, 0, 0); }
;                   else { p0 = __builtin_amdgcn_mfma_f32_32x32x16_bf16(b0, qr[d0], p0, 0, 0, 0); p1 = __builtin_amdgcn_mfma_f32_32x32x16_bf16(b1, qr[d0], p1, 0, 0, 0); } } }
;             if (MODE == 1) {
;                 const ATT_LAS float* bp = bias_l + (64 * t - (qw + r32) + 256 + 4 * hi);
; #pragma unroll
;                 for (int r = 0; r < 16; ++r) { p0[r] += bp[(r & 3) + 8 * (r >> 2)]; p1[r] += bp[(r & 3) + 8 * (r >> 2) + 32]; }
;             }
;             asm volatile("s_nop 15\n\ts_nop 7" : "+v"(p0), "+v"(p1));
;             float rm, rmb;
;             rm = max3f(p0[0], p0[1], p1[0]); rmb = max3f(p0[2], p0[3], p1[1]); rm = max3f(rm, p1[2], p1[3]);
; #pragma unroll
;             for (int r = 4; r < 16; r += 4) { rm = max3f(rm, p0[r], p0[r + 1]); rmb = max3f(rmb, p0[r + 2], p0[r + 3]); rm = max3f(rm, p1[r], p1[r + 1]); rmb = max3f(rmb, p1[r + 2], p1[r + 3]); }
;             rm = max2f(rm, rmb);
;             { auto rr = __builtin_amdgcn_permlane32_swap(__float_as_uint(rm), __float_as_uint(rm), false, false); rm = max2f(__uint_as_float(rr[0]), __uint_as_float(rr[1])); }
;             const bool first = (t == wt0);
;             if (first) {
;                 mhat = rm;
; #pragma unroll
;                 for (int r = 0; r < 16; ++r) { p0[r] -= rm; p1[r] -= rm; }
; #pragma unroll
;                 for (int r = 0; r < 16; ++r) negm[r] = -mhat;
;             } else if (__any(rm > THR)) {
;                 const float dl = fmaxf(rm, 0.f); mhat += dl;
; #pragma unroll
;                 for (int r = 0; r < 16; ++r) { p0[r] -= dl; p1[r] -= dl; }
; #pragma unroll
;                 for (int r = 0; r < 16; ++r) negm[r] = -mhat;
.LBB0_612:
	s_cmp_ge_i32 s47, s51
	s_cselect_b64 s[42:43], -1, 0
	s_cmp_le_i32 s47, s54
	s_cselect_b64 s[60:61], -1, 0
	s_and_b64 s[42:43], s[42:43], s[60:61]
	s_andn2_b64 vcc, exec, s[42:43]
	s_cbranch_vccnz .LBB0_605
	s_lshl_b32 s41, s50, 13
	v_add_u32_e32 v0, s41, v211
	ds_read_b128 v[216:219], v0
	ds_read_b128 v[220:223], v0 offset:512
	ds_read_b128 v[224:227], v0 offset:2048
	ds_read_b128 v[234:237], v0 offset:2560
	ds_read_b128 v[238:241], v0 offset:4096
	ds_read_b128 v[242:245], v0 offset:4608
	ds_read_b128 v[246:249], v0 offset:6144
	ds_read_b128 v[250:253], v0 offset:6656
	s_cmp_lg_u32 s51, s47
	s_waitcnt lgkmcnt(7)
	v_mfma_f32_32x32x16_bf16 v[50:65], v[216:219], v[192:195], v[68:83]
	s_waitcnt lgkmcnt(6)
	v_mfma_f32_32x32x16_bf16 v[34:49], v[220:223], v[192:195], v[68:83]
	s_waitcnt lgkmcnt(5)
	v_mfma_f32_32x32x16_bf16 v[50:65], v[224:227], v[188:191], v[50:65]
	s_waitcnt lgkmcnt(4)
	v_mfma_f32_32x32x16_bf16 v[34:49], v[234:237], v[188:191], v[34:49]
	s_waitcnt lgkmcnt(3)
	v_mfma_f32_32x32x16_bf16 v[50:65], v[238:241], v[180:183], v[50:65]
	s_waitcnt lgkmcnt(2)
	v_mfma_f32_32x32x16_bf16 v[34:49], v[242:245], v[180:183], v[34:49]
	s_waitcnt lgkmcnt(1)
	v_mfma_f32_32x32x16_bf16 v[50:65], v[246:249], v[184:187], v[50:65]
	s_waitcnt lgkmcnt(0)
	v_mfma_f32_32x32x16_bf16 v[34:49], v[250:253], v[184:187], v[34:49]
	ds_read2_b32 v[100:101], v212 offset1:1
	ds_read2_b32 v[102:103], v212 offset0:32 offset1:33
	ds_read2_b32 v[104:105], v212 offset0:2 offset1:3
	ds_read2_b32 v[106:107], v212 offset0:34 offset1:35
	ds_read2_b32 v[108:109], v212 offset0:8 offset1:9
	ds_read2_b32 v[110:111], v212 offset0:40 offset1:41
	ds_read2_b32 v[112:113], v212 offset0:10 offset1:11
	ds_read2_b32 v[114:115], v212 offset0:42 offset1:43
	ds_read2_b32 v[116:117], v212 offset0:16 offset1:17
	ds_read2_b32 v[132:133], v212 offset0:48 offset1:49
	ds_read2_b32 v[118:119], v212 offset0:18 offset1:19
	ds_read2_b32 v[134:135], v212 offset0:50 offset1:51
	ds_read2_b32 v[120:121], v212 offset0:24 offset1:25
	ds_read2_b32 v[136:137], v212 offset0:56 offset1:57
	ds_read2_b32 v[122:123], v212 offset0:26 offset1:27
	s_waitcnt lgkmcnt(6)
	v_pk_add_f32 v[124:125], v[58:59], v[116:117]
	v_pk_add_f32 v[116:117], v[50:51], v[100:101]
	ds_read2_b32 v[50:51], v212 offset0:58 offset1:59
	s_waitcnt lgkmcnt(3)
	v_pk_add_f32 v[128:129], v[62:63], v[120:121]
	s_waitcnt lgkmcnt(1)
	v_pk_add_f32 v[130:131], v[64:65], v[122:123]
	v_pk_add_f32 v[126:127], v[60:61], v[118:119]
	v_pk_add_f32 v[122:123], v[56:57], v[112:113]
	v_pk_add_f32 v[120:121], v[54:55], v[108:109]
	v_pk_add_f32 v[118:119], v[52:53], v[104:105]
	s_waitcnt lgkmcnt(0)
	v_pk_add_f32 v[146:147], v[48:49], v[50:51]
	v_pk_add_f32 v[144:145], v[46:47], v[136:137]
	v_pk_add_f32 v[142:143], v[44:45], v[134:135]
	v_pk_add_f32 v[140:141], v[42:43], v[132:133]
	v_pk_add_f32 v[138:139], v[40:41], v[114:115]
	v_pk_add_f32 v[136:137], v[38:39], v[110:111]
	v_pk_add_f32 v[134:135], v[36:37], v[106:107]
	v_pk_add_f32 v[132:133], v[34:35], v[102:103]
	s_nop 0
	s_nop 15
	s_nop 7
	s_nop 0
	v_max3_f32 v0, v116, v117, v132
	v_max3_f32 v34, v118, v119, v133
	s_nop 0
	v_max3_f32 v0, v0, v134, v135
	v_max3_f32 v34, v34, v122, v123
	s_nop 0
	v_max3_f32 v0, v0, v120, v121
	v_max3_f32 v34, v34, v138, v139
	s_nop 0
	v_max3_f32 v0, v0, v136, v137
	v_max3_f32 v34, v34, v126, v127
	s_nop 0
	v_max3_f32 v0, v0, v124, v125
	v_max3_f32 v34, v34, v142, v143
	s_nop 0
	v_max3_f32 v0, v0, v140, v141
	v_max3_f32 v34, v34, v130, v131
	s_nop 0
	v_max3_f32 v0, v0, v128, v129
	v_max3_f32 v34, v34, v146, v147
	s_nop 0
	v_max3_f32 v0, v0, v144, v145
	s_nop 0
	v_max_f32_e32 v0, v0, v34
	s_nop 0
	v_mov_b32_e32 v34, v0
	s_nop 1
	v_permlane32_swap_b32_e32 v0, v34
	v_max_f32_e32 v0, v0, v34
	s_cbranch_scc0 .LBB0_618
	v_cmp_lt_f32_e32 vcc, s70, v0
	s_cbranch_vccz .LBB0_619
	v_max_f32_e32 v34, v0, v0
	v_max_f32_e32 v34, 0, v34
	s_and_saveexec_b64 s[42:43], s[4:5]
	v_exp_f32_e64 v35, -v34
	ds_write_b32 v210, v35 offset:40960
	s_or_b64 exec, exec, s[42:43]
	s_waitcnt lgkmcnt(0)
	ds_read_b128 v[38:41], v209 offset:41024
	ds_read_b128 v[42:45], v209 offset:41056
	ds_read_b128 v[68:71], v209 offset:40960
	ds_read_b128 v[72:75], v209 offset:40992
	s_waitcnt lgkmcnt(0)
	v_add_f32_e32 v66, v66, v34
	v_xor_b32_e32 v83, 0x80000000, v66
	v_sub_f32_e32 v163, v131, v34
	v_sub_f32_e32 v162, v130, v34
	v_sub_f32_e32 v161, v129, v34
	v_sub_f32_e32 v160, v128, v34
	v_sub_f32_e32 v159, v127, v34
	v_sub_f32_e32 v158, v126, v34
	v_sub_f32_e32 v157, v125, v34
	v_sub_f32_e32 v156, v124, v34
	v_sub_f32_e32 v155, v123, v34
	v_sub_f32_e32 v154, v122, v34
	v_sub_f32_e32 v153, v121, v34
	v_sub_f32_e32 v152, v120, v34
	v_sub_f32_e32 v151, v119, v34
	v_sub_f32_e32 v150, v118, v34
	v_sub_f32_e32 v149, v117, v34
	v_sub_f32_e32 v148, v116, v34
	v_sub_f32_e32 v179, v147, v34
	v_sub_f32_e32 v178, v146, v34
	v_sub_f32_e32 v177, v145, v34
	v_sub_f32_e32 v176, v144, v34
	v_sub_f32_e32 v175, v143, v34
	v_sub_f32_e32 v174, v142, v34
	v_sub_f32_e32 v173, v141, v34
	v_sub_f32_e32 v172, v140, v34
	v_sub_f32_e32 v171, v139, v34
	v_sub_f32_e32 v170, v138, v34
	v_sub_f32_e32 v169, v137, v34
	v_sub_f32_e32 v168, v136, v34
	v_sub_f32_e32 v167, v135, v34
	v_sub_f32_e32 v166, v134, v34
	v_sub_f32_e32 v165, v133, v34
	v_sub_f32_e32 v164, v132, v34
	s_waitcnt lgkmcnt(2)
	v_pk_mul_f32 v[114:115], v[98:99], v[44:45]
	v_pk_mul_f32 v[110:111], v[94:95], v[40:41]
	s_waitcnt lgkmcnt(0)
	v_pk_mul_f32 v[106:107], v[90:91], v[74:75]
	v_pk_mul_f32 v[102:103], v[86:87], v[70:71]
	v_pk_mul_f32 v[112:113], v[96:97], v[42:43]
	v_pk_mul_f32 v[108:109], v[92:93], v[38:39]
	v_pk_mul_f32 v[104:105], v[88:89], v[72:73]
	v_pk_mul_f32 v[100:101], v[84:85], v[68:69]
	v_pk_mul_f32 v[64:65], v[32:33], v[44:45]
	v_pk_mul_f32 v[60:61], v[28:29], v[40:41]
	v_pk_mul_f32 v[56:57], v[24:25], v[74:75]
	v_pk_mul_f32 v[52:53], v[20:21], v[70:71]
	v_pk_mul_f32 v[48:49], v[16:17], v[44:45]
	v_pk_mul_f32 v[44:45], v[12:13], v[40:41]
	v_pk_mul_f32 v[40:41], v[8:9], v[74:75]
	v_pk_mul_f32 v[36:37], v[4:5], v[70:71]
	v_pk_mul_f32 v[62:63], v[30:31], v[42:43]
	v_pk_mul_f32 v[58:59], v[26:27], v[38:39]
	v_pk_mul_f32 v[54:55], v[22:23], v[72:73]
	v_pk_mul_f32 v[50:51], v[18:19], v[68:69]
	v_pk_mul_f32 v[46:47], v[14:15], v[42:43]
	v_pk_mul_f32 v[42:43], v[10:11], v[38:39]
	v_pk_mul_f32 v[38:39], v[6:7], v[72:73]
	v_pk_mul_f32 v[34:35], v[2:3], v[68:69]
	v_mov_b32_e32 v82, v83
	v_mov_b32_e32 v81, v83
	v_mov_b32_e32 v80, v83
	v_mov_b32_e32 v79, v83
	v_mov_b32_e32 v78, v83
	v_mov_b32_e32 v77, v83
	v_mov_b32_e32 v76, v83
	v_mov_b32_e32 v75, v83
	v_mov_b32_e32 v74, v83
	v_mov_b32_e32 v73, v83
	v_mov_b32_e32 v72, v83
	v_mov_b32_e32 v71, v83
	v_mov_b32_e32 v70, v83
	v_mov_b32_e32 v69, v83
	v_mov_b32_e32 v68, v83
	s_cbranch_execnz .LBB0_604
	s_branch .LBB0_603
